# v55 + compress-GEMM epilogue: the three bias loads serialised behind the stores issued with the first one (free VGPR quads, copied into the original registers at the original positions)
# baseline (speedup 1.0000x reference)
; template <class AP, class BP>
; DI void gemm_accum(f32x4 (&acc)[4][4], AP ap, BP bp, int nkb, bf16_t* lds) {
;     ...
;   for (int kb = 0; kb < nkb; kb += 2) {
;     const int k2 = (kb + 2 < nkb) ? kb + 2 : nkb - 2;
;     g_load(ra0, rb0, ap, bp, k2, lrow, lch);
;     __builtin_amdgcn_sched_barrier(0);
;     g_compute(acc, As, Bs, wm, wn, lane);
;     g_store(As, Bs, ra1, rb1, 1, lrow, lch);
;     __syncthreads();
; __global__ void __launch_bounds__(512, 2) mega(Params p) {
;     ...
;         auto ap = [&](int r, int kb) -> const bf16_t* {
;           int row = m0 + r;
;           int bg = row >> 9, c = row & 511;
;           int tk = 16 * c + kb;
;           tk = tk > (SEQ - 1) ? (SEQ - 1) : tk;
;           return kvd + ((size_t)(bg * SEQ + tk)) * 64;
;         };
.LBB0_269:
	s_add_i32 s12, s20, 2
	s_cmp_lt_u32 s20, 30
	s_cselect_b64 s[20:21], -1, 0
	s_and_b64 vcc, s[20:21], exec
	s_cselect_b32 s13, s12, 30
	v_add_u32_e32 v98, s13, v131
	v_add_u32_e32 v106, s13, v0
	v_add_u32_e32 v138, s13, v134
	v_add_u32_e32 v148, s13, v136
	v_min_u32_e32 v98, 0x1fff, v98
	v_min_u32_e32 v106, 0x1fff, v106
	v_min_u32_e32 v138, 0x1fff, v138
	v_min_u32_e32 v148, 0x1fff, v148
	v_or_b32_e32 v98, v98, v132
	v_or_b32_e32 v106, v106, v133
	v_or_b32_e32 v138, v138, v135
	v_or_b32_e32 v148, v148, v137
	s_lshl_b32 s28, s13, 7
	v_ashrrev_i32_e32 v99, 31, v98
	v_ashrrev_i32_e32 v107, 31, v106
	v_ashrrev_i32_e32 v139, 31, v138
	v_ashrrev_i32_e32 v149, 31, v148
	v_lshl_add_u64 v[146:147], v[114:115], 0, s[28:29]
	v_lshlrev_b64 v[98:99], 7, v[98:99]
	v_lshlrev_b64 v[106:107], 7, v[106:107]
	v_lshlrev_b64 v[138:139], 7, v[138:139]
	v_lshlrev_b64 v[148:149], 7, v[148:149]
	v_lshl_add_u64 v[98:99], v[116:117], 0, v[98:99]
	v_lshl_add_u64 v[102:103], v[146:147], 0, v[118:119]
	v_lshl_add_u64 v[106:107], v[116:117], 0, v[106:107]
	v_lshl_add_u64 v[110:111], v[146:147], 0, v[120:121]
	v_lshl_add_u64 v[138:139], v[116:117], 0, v[138:139]
	v_lshl_add_u64 v[142:143], v[146:147], 0, v[122:123]
	v_lshl_add_u64 v[148:149], v[116:117], 0, v[148:149]
	v_lshl_add_u64 v[150:151], v[146:147], 0, v[124:125]
	global_load_dwordx4 v[98:101], v[98:99], off
	s_nop 0
	global_load_dwordx4 v[102:105], v[102:103], off
	s_nop 0
	global_load_dwordx4 v[106:109], v[106:107], off
	s_nop 0
	global_load_dwordx4 v[110:113], v[110:111], off
	s_nop 0
	global_load_dwordx4 v[138:141], v[138:139], off
	s_nop 0
	global_load_dwordx4 v[142:145], v[142:143], off
	s_nop 0
	global_load_dwordx4 v[146:149], v[148:149], off
	s_nop 0
	global_load_dwordx4 v[150:153], v[150:151], off
	ds_read_b128 v[154:157], v127
	ds_read_b128 v[158:161], v127 offset:2048
	ds_read_b128 v[164:167], v128 offset:32768
	ds_read_b128 v[168:171], v128 offset:34816
	ds_read_b128 v[172:175], v127 offset:4096
	ds_read_b128 v[176:179], v127 offset:6144
	ds_read_b128 v[180:183], v128 offset:36864
	ds_read_b128 v[184:187], v128 offset:38912
	ds_read_b128 v[188:191], v129
	ds_read_b128 v[192:195], v129 offset:2048
	ds_read_b128 v[206:209], v130 offset:32768
	ds_read_b128 v[210:213], v130 offset:34816
	ds_read_b128 v[214:217], v129 offset:4096
	ds_read_b128 v[218:221], v129 offset:6144
	ds_read_b128 v[222:225], v130 offset:36864
	ds_read_b128 v[226:229], v130 offset:38912
	s_waitcnt lgkmcnt(13)
	v_mfma_f32_16x16x32_bf16 v[94:97], v[164:167], v[154:157], v[94:97]
	s_waitcnt lgkmcnt(12)
	v_mfma_f32_16x16x32_bf16 v[50:53], v[168:171], v[154:157], v[50:53]
	s_waitcnt lgkmcnt(9)
	v_mfma_f32_16x16x32_bf16 v[46:49], v[180:183], v[154:157], v[46:49]
	s_waitcnt lgkmcnt(8)
	v_mfma_f32_16x16x32_bf16 v[66:69], v[184:187], v[154:157], v[66:69]
	v_mfma_f32_16x16x32_bf16 v[62:65], v[164:167], v[158:161], v[62:65]
	v_mfma_f32_16x16x32_bf16 v[58:61], v[168:171], v[158:161], v[58:61]
	v_mfma_f32_16x16x32_bf16 v[54:57], v[180:183], v[158:161], v[54:57]
	v_mfma_f32_16x16x32_bf16 v[42:45], v[184:187], v[158:161], v[42:45]
	v_mfma_f32_16x16x32_bf16 v[34:37], v[164:167], v[172:175], v[34:37]
	v_mfma_f32_16x16x32_bf16 v[26:29], v[168:171], v[172:175], v[26:29]
	v_mfma_f32_16x16x32_bf16 v[22:25], v[180:183], v[172:175], v[22:25]
	v_mfma_f32_16x16x32_bf16 v[18:21], v[184:187], v[172:175], v[18:21]
	v_mfma_f32_16x16x32_bf16 v[14:17], v[164:167], v[176:179], v[14:17]
	v_mfma_f32_16x16x32_bf16 v[10:13], v[168:171], v[176:179], v[10:13]
	v_mfma_f32_16x16x32_bf16 v[6:9], v[180:183], v[176:179], v[6:9]
	v_mfma_f32_16x16x32_bf16 v[2:5], v[184:187], v[176:179], v[2:5]
	s_waitcnt lgkmcnt(5)
	v_mfma_f32_16x16x32_bf16 v[94:97], v[206:209], v[188:191], v[94:97]
	s_waitcnt lgkmcnt(4)
	v_mfma_f32_16x16x32_bf16 v[50:53], v[210:213], v[188:191], v[50:53]
	s_waitcnt lgkmcnt(1)
	v_mfma_f32_16x16x32_bf16 v[46:49], v[222:225], v[188:191], v[46:49]
	s_waitcnt lgkmcnt(0)
	v_mfma_f32_16x16x32_bf16 v[66:69], v[226:229], v[188:191], v[66:69]
	v_mfma_f32_16x16x32_bf16 v[62:65], v[206:209], v[192:195], v[62:65]
	v_mfma_f32_16x16x32_bf16 v[58:61], v[210:213], v[192:195], v[58:61]
	v_mfma_f32_16x16x32_bf16 v[54:57], v[222:225], v[192:195], v[54:57]
	v_mfma_f32_16x16x32_bf16 v[42:45], v[226:229], v[192:195], v[42:45]
	v_mfma_f32_16x16x32_bf16 v[34:37], v[206:209], v[214:217], v[34:37]
	v_mfma_f32_16x16x32_bf16 v[26:29], v[210:213], v[214:217], v[26:29]
	v_mfma_f32_16x16x32_bf16 v[22:25], v[222:225], v[214:217], v[22:25]
	v_mfma_f32_16x16x32_bf16 v[18:21], v[226:229], v[214:217], v[18:21]
	v_mfma_f32_16x16x32_bf16 v[14:17], v[206:209], v[218:221], v[14:17]
	v_mfma_f32_16x16x32_bf16 v[10:13], v[210:213], v[218:221], v[10:13]
	v_mfma_f32_16x16x32_bf16 v[6:9], v[222:225], v[218:221], v[6:9]
	v_mfma_f32_16x16x32_bf16 v[2:5], v[226:229], v[218:221], v[2:5]
	s_or_b32 s13, s13, 1
	s_waitcnt vmcnt(14)
	ds_write_b128 v126, v[30:33] offset:16384
	ds_write_b128 v126, v[38:41] offset:49152
	s_waitcnt vmcnt(13)
	ds_write_b128 v126, v[70:73] offset:20480
	s_waitcnt vmcnt(12)
	ds_write_b128 v126, v[74:77] offset:53248
	s_waitcnt vmcnt(10)
	ds_write_b128 v126, v[82:85] offset:24576
	ds_write_b128 v126, v[78:81] offset:57344
	s_waitcnt vmcnt(9)
	ds_write_b128 v126, v[86:89] offset:28672
	s_waitcnt vmcnt(8)
	ds_write_b128 v126, v[90:93] offset:61440
	v_add_u32_e32 v32, s13, v131
	v_add_u32_e32 v33, s13, v0
	v_add_u32_e32 v38, s13, v134
	v_add_u32_e32 v39, s13, v136
	v_min_u32_e32 v32, 0x1fff, v32
	v_min_u32_e32 v33, 0x1fff, v33
	v_min_u32_e32 v41, 0x1fff, v38
	v_min_u32_e32 v71, 0x1fff, v39
	s_lshl_b32 s28, s13, 7
	v_or_b32_e32 v32, v32, v132
	v_or_b32_e32 v40, v33, v133
	v_or_b32_e32 v70, v41, v135
	v_or_b32_e32 v72, v71, v137
	v_lshl_add_u64 v[30:31], v[114:115], 0, s[28:29]
	v_ashrrev_i32_e32 v33, 31, v32
	v_ashrrev_i32_e32 v41, 31, v40
	v_ashrrev_i32_e32 v71, 31, v70
	v_ashrrev_i32_e32 v73, 31, v72
	v_lshl_add_u64 v[38:39], v[30:31], 0, v[118:119]
	v_lshl_add_u64 v[74:75], v[30:31], 0, v[120:121]
	v_lshl_add_u64 v[78:79], v[30:31], 0, v[122:123]
	v_lshl_add_u64 v[90:91], v[30:31], 0, v[124:125]
	v_lshlrev_b64 v[30:31], 7, v[32:33]
	v_lshlrev_b64 v[32:33], 7, v[40:41]
	v_lshlrev_b64 v[40:41], 7, v[70:71]
	v_lshlrev_b64 v[70:71], 7, v[72:73]
	v_lshl_add_u64 v[30:31], v[116:117], 0, v[30:31]
	v_lshl_add_u64 v[72:73], v[116:117], 0, v[32:33]
	v_lshl_add_u64 v[80:81], v[116:117], 0, v[40:41]
	v_lshl_add_u64 v[86:87], v[116:117], 0, v[70:71]
	s_waitcnt lgkmcnt(0)
	s_barrier
; template <class AP, class BP>
; DI void gemm_accum(f32x4 (&acc)[4][4], AP ap, BP bp, int nkb, bf16_t* lds) {
;     ...
;     g_load(ra1, rb1, ap, bp, k2 + 1, lrow, lch);
;     __builtin_amdgcn_sched_barrier(0);
;     g_compute(acc, As + 8192, Bs + 8192, wm, wn, lane);
;     g_store(As, Bs, ra0, rb0, 0, lrow, lch);
;     __syncthreads();
;   }
; __global__ void __launch_bounds__(512, 2) mega(Params p) {
;     ...
;         const float* bs = bias + kv * 256;
;         bf16_t* hd = hid + (size_t)kv * 4096 * 256;
	global_load_dwordx4 v[30:33], v[30:31], off
	s_nop 0
	global_load_dwordx4 v[38:41], v[38:39], off
	s_nop 0
	global_load_dwordx4 v[70:73], v[72:73], off
	s_nop 0
	global_load_dwordx4 v[74:77], v[74:75], off
	s_nop 0
	global_load_dwordx4 v[82:85], v[80:81], off
	s_nop 0
	global_load_dwordx4 v[78:81], v[78:79], off
	s_nop 0
	global_load_dwordx4 v[86:89], v[86:87], off
	s_nop 0
	global_load_dwordx4 v[90:93], v[90:91], off
	ds_read_b128 v[154:157], v127 offset:16384
	ds_read_b128 v[158:161], v127 offset:18432
	ds_read_b128 v[164:167], v128 offset:49152
	ds_read_b128 v[168:171], v128 offset:51200
	ds_read_b128 v[172:175], v127 offset:20480
	ds_read_b128 v[176:179], v127 offset:22528
	ds_read_b128 v[180:183], v128 offset:53248
	ds_read_b128 v[184:187], v128 offset:55296
	ds_read_b128 v[188:191], v129 offset:16384
	ds_read_b128 v[192:195], v129 offset:18432
	ds_read_b128 v[206:209], v130 offset:49152
	ds_read_b128 v[210:213], v130 offset:51200
	ds_read_b128 v[214:217], v129 offset:20480
	ds_read_b128 v[218:221], v129 offset:22528
	ds_read_b128 v[222:225], v130 offset:53248
	ds_read_b128 v[226:229], v130 offset:55296
	s_waitcnt lgkmcnt(13)
	v_mfma_f32_16x16x32_bf16 v[94:97], v[164:167], v[154:157], v[94:97]
	s_waitcnt lgkmcnt(12)
	v_mfma_f32_16x16x32_bf16 v[50:53], v[168:171], v[154:157], v[50:53]
	s_waitcnt lgkmcnt(9)
	v_mfma_f32_16x16x32_bf16 v[46:49], v[180:183], v[154:157], v[46:49]
	s_waitcnt lgkmcnt(8)
	v_mfma_f32_16x16x32_bf16 v[66:69], v[184:187], v[154:157], v[66:69]
	v_mfma_f32_16x16x32_bf16 v[62:65], v[164:167], v[158:161], v[62:65]
	v_mfma_f32_16x16x32_bf16 v[58:61], v[168:171], v[158:161], v[58:61]
	v_mfma_f32_16x16x32_bf16 v[54:57], v[180:183], v[158:161], v[54:57]
	v_mfma_f32_16x16x32_bf16 v[42:45], v[184:187], v[158:161], v[42:45]
	v_mfma_f32_16x16x32_bf16 v[34:37], v[164:167], v[172:175], v[34:37]
	v_mfma_f32_16x16x32_bf16 v[26:29], v[168:171], v[172:175], v[26:29]
	v_mfma_f32_16x16x32_bf16 v[22:25], v[180:183], v[172:175], v[22:25]
	v_mfma_f32_16x16x32_bf16 v[18:21], v[184:187], v[172:175], v[18:21]
	v_mfma_f32_16x16x32_bf16 v[14:17], v[164:167], v[176:179], v[14:17]
	v_mfma_f32_16x16x32_bf16 v[10:13], v[168:171], v[176:179], v[10:13]
	v_mfma_f32_16x16x32_bf16 v[6:9], v[180:183], v[176:179], v[6:9]
	v_mfma_f32_16x16x32_bf16 v[2:5], v[184:187], v[176:179], v[2:5]
	s_waitcnt lgkmcnt(5)
	v_mfma_f32_16x16x32_bf16 v[94:97], v[206:209], v[188:191], v[94:97]
	s_waitcnt lgkmcnt(4)
	v_mfma_f32_16x16x32_bf16 v[50:53], v[210:213], v[188:191], v[50:53]
	s_waitcnt lgkmcnt(1)
	v_mfma_f32_16x16x32_bf16 v[46:49], v[222:225], v[188:191], v[46:49]
	s_waitcnt lgkmcnt(0)
	v_mfma_f32_16x16x32_bf16 v[66:69], v[226:229], v[188:191], v[66:69]
	v_mfma_f32_16x16x32_bf16 v[62:65], v[206:209], v[192:195], v[62:65]
	v_mfma_f32_16x16x32_bf16 v[58:61], v[210:213], v[192:195], v[58:61]
	v_mfma_f32_16x16x32_bf16 v[54:57], v[222:225], v[192:195], v[54:57]
	v_mfma_f32_16x16x32_bf16 v[42:45], v[226:229], v[192:195], v[42:45]
	v_mfma_f32_16x16x32_bf16 v[34:37], v[206:209], v[214:217], v[34:37]
	v_mfma_f32_16x16x32_bf16 v[26:29], v[210:213], v[214:217], v[26:29]
	v_mfma_f32_16x16x32_bf16 v[22:25], v[222:225], v[214:217], v[22:25]
	v_mfma_f32_16x16x32_bf16 v[18:21], v[226:229], v[214:217], v[18:21]
	v_mfma_f32_16x16x32_bf16 v[14:17], v[206:209], v[218:221], v[14:17]
	v_mfma_f32_16x16x32_bf16 v[10:13], v[210:213], v[218:221], v[10:13]
	v_mfma_f32_16x16x32_bf16 v[6:9], v[222:225], v[218:221], v[6:9]
	v_mfma_f32_16x16x32_bf16 v[2:5], v[226:229], v[218:221], v[2:5]
	s_mov_b32 s20, s12
	s_waitcnt vmcnt(15)
	ds_write_b128 v126, v[98:101]
	s_waitcnt vmcnt(14)
	ds_write_b128 v126, v[102:105] offset:32768
	s_waitcnt vmcnt(13)
	ds_write_b128 v126, v[106:109] offset:4096
	s_waitcnt vmcnt(12)
	ds_write_b128 v126, v[110:113] offset:36864
	s_waitcnt vmcnt(11)
	ds_write_b128 v126, v[138:141] offset:8192
	s_waitcnt vmcnt(10)
	ds_write_b128 v126, v[142:145] offset:40960
	s_waitcnt vmcnt(9)
	ds_write_b128 v126, v[146:149] offset:12288
	s_waitcnt vmcnt(8)
	ds_write_b128 v126, v[150:153] offset:45056
	s_waitcnt lgkmcnt(0)
	s_barrier
	s_cbranch_vccnz .LBB0_269
	v_and_b32_e32 v0, 0xff, v196
	s_lshl_b32 s12, s2, 8
	s_ashr_i32 s13, s12, 31
	s_waitcnt vmcnt(7)
	v_ashrrev_i32_e32 v31, 1, v0
	v_and_b32_e32 v30, 64, v0
	v_and_b32_e32 v31, 0xffffffc0, v31
	v_and_or_b32 v32, v0, 15, s9
	v_lshrrev_b32_e32 v0, 2, v0
	s_lshl_b64 s[12:13], s[12:13], 2
	v_readlane_b32 s20, v251, 53
	s_waitcnt vmcnt(5)
	v_add_u32_e32 v70, v32, v31
	v_and_b32_e32 v0, 12, v0
	v_readlane_b32 s21, v251, 54
	s_add_u32 s12, s20, s12
	v_or3_b32 v0, v30, v0, s7
	v_ashrrev_i32_e32 v71, 31, v70
	s_addc_u32 s13, s21, s13
	v_lshlrev_b64 v[40:41], 9, v[70:71]
	v_lshlrev_b32_e32 v71, 2, v0
	global_load_dwordx4 v[30:33], v71, s[12:13]
	global_load_dwordx4 v[112:115], v71, s[12:13] offset:64
	global_load_dwordx4 v[116:119], v71, s[12:13] offset:128
	global_load_dwordx4 v[120:123], v71, s[12:13] offset:192
	s_lshl_b64 s[2:3], s[2:3], 21
	s_add_u32 s2, s44, s2
	s_addc_u32 s3, s45, s3
	v_lshl_add_u64 v[40:41], s[2:3], 0, v[40:41]
	v_lshlrev_b32_e32 v0, 1, v0
	s_mov_b32 s9, 0x800000
	s_waitcnt vmcnt(3)
; DI int TID() { int t = threadIdx.x & 255; asm volatile("" : "+v"(t)); return t; }
; template <class E>
; DI void gemm_epi(f32x4 (&acc)[4][4], int m0, int n0, E e) {
;   const int tid_ = TID();
;   const int lane = tid_ & 63, w = tid_ >> 6;
;   const int wm = w >> 1, wn = w & 1;
; #pragma unroll
;   for (int i = 0; i < 4; ++i)
; #pragma unroll
;     for (int j = 0; j < 4; ++j) {
;       int m = m0 + wm * 64 + i * 16 + (lane & 15);
;       int n = n0 + wn * 64 + j * 16 + (lane >> 4) * 4;
;       e(m, n, acc[i][j]);
;     }
; }
; __global__ void __launch_bounds__(512, 2) mega(Params p) {
;     ...
;         gemm_epi(acc, m0, n0, [&](int m, int n, f32x4& a) {
;           float o[4];
; #pragma unroll
;           for (int j = 0; j < 4; ++j) {
;             float xv = a[j] + bs[n + j];
;             float y = 0.7978845608028654f * (xv + 0.044715f * xv * xv * xv);
;             float th = 1.f - 2.f * __builtin_amdgcn_rcpf(__expf(2.f * y) + 1.f);
;             o[j] = 0.5f * xv * (1.f + th);
;           }
;           uint2 u;
;           u.x = pack2(o[0], o[1]);
;           u.y = pack2(o[2], o[3]);
;           *(uint2*)(hd + (size_t)m * 256 + n) = u;
;         });
	v_pk_add_f32 v[38:39], v[94:95], v[30:31]
	s_nop 0
	v_mul_f32_e32 v72, 0x3d372713, v38
	v_mul_f32_e32 v73, 0x3d372713, v39
	v_mul_f32_e32 v72, v38, v72
	v_mul_f32_e32 v73, v39, v73
	v_fma_f32 v72, v38, v72, v38
	v_fma_f32 v73, v39, v73, v39
	v_mul_f32_e32 v72, 0x3f4c422a, v72
	v_mul_f32_e32 v73, 0x3f4c422a, v73
	v_add_f32_e32 v72, v72, v72
	v_add_f32_e32 v73, v73, v73
	v_mul_f32_e32 v72, 0x3fb8aa3b, v72
	v_mul_f32_e32 v73, 0x3fb8aa3b, v73
	v_exp_f32_e32 v72, v72
	v_exp_f32_e32 v73, v73
	v_pk_mul_f32 v[38:39], v[38:39], 0.5 op_sel_hi:[1,0]
	v_pk_add_f32 v[62:63], v[62:63], v[30:31]
	v_add_f32_e32 v72, 1.0, v72
	v_add_f32_e32 v73, 1.0, v73
	v_rcp_f32_e32 v72, v72
	v_rcp_f32_e32 v73, v73
	v_pk_add_f32 v[64:65], v[64:65], v[32:33]
	v_pk_add_f32 v[34:35], v[34:35], v[30:31]
	v_pk_add_f32 v[36:37], v[36:37], v[32:33]
	v_pk_fma_f32 v[72:73], v[72:73], 2.0, 1.0 op_sel_hi:[1,0,0] neg_lo:[1,0,0] neg_hi:[1,0,0]
	v_pk_add_f32 v[14:15], v[14:15], v[30:31]
	v_pk_add_f32 v[72:73], v[72:73], 1.0 op_sel_hi:[1,0]
	v_pk_add_f32 v[16:17], v[16:17], v[32:33]
	v_pk_mul_f32 v[38:39], v[38:39], v[72:73]
	v_pk_add_f32 v[72:73], v[96:97], v[32:33]
	v_cvt_pk_bf16_f32 v38, v38, v39
	v_mul_f32_e32 v74, 0x3d372713, v72
	v_mul_f32_e32 v75, 0x3d372713, v73
	v_mul_f32_e32 v74, v72, v74
	v_mul_f32_e32 v75, v73, v75
	v_fma_f32 v74, v72, v74, v72
	v_fma_f32 v75, v73, v75, v73
	v_mul_f32_e32 v74, 0x3f4c422a, v74
	v_mul_f32_e32 v75, 0x3f4c422a, v75
	v_add_f32_e32 v74, v74, v74
	v_add_f32_e32 v75, v75, v75
	v_mul_f32_e32 v74, 0x3fb8aa3b, v74
	v_mul_f32_e32 v75, 0x3fb8aa3b, v75
	v_exp_f32_e32 v74, v74
	v_exp_f32_e32 v75, v75
	v_pk_mul_f32 v[72:73], v[72:73], 0.5 op_sel_hi:[1,0]
	v_add_f32_e32 v74, 1.0, v74
	v_add_f32_e32 v75, 1.0, v75
	v_rcp_f32_e32 v74, v74
	v_rcp_f32_e32 v75, v75
	s_nop 0
	v_pk_fma_f32 v[74:75], v[74:75], 2.0, 1.0 op_sel_hi:[1,0,0] neg_lo:[1,0,0] neg_hi:[1,0,0]
	s_nop 0
	v_pk_add_f32 v[74:75], v[74:75], 1.0 op_sel_hi:[1,0]
	s_nop 0
	v_pk_mul_f32 v[72:73], v[72:73], v[74:75]
	s_nop 0
	v_cvt_pk_bf16_f32 v39, v72, v73
	v_lshl_add_u64 v[72:73], v[40:41], 0, v[0:1]
	global_store_dwordx2 v[72:73], v[38:39], off
	s_waitcnt vmcnt(3)
	v_mov_b64_e32 v[38:39], v[112:113]
	v_mov_b64_e32 v[40:41], v[114:115]
	v_pk_add_f32 v[50:51], v[50:51], v[38:39]
	s_nop 0
	v_mul_f32_e32 v74, 0x3d372713, v50
	v_mul_f32_e32 v75, 0x3d372713, v51
	v_mul_f32_e32 v74, v50, v74
	v_mul_f32_e32 v75, v51, v75
	v_fma_f32 v74, v50, v74, v50
	v_fma_f32 v75, v51, v75, v51
	v_mul_f32_e32 v74, 0x3f4c422a, v74
	v_mul_f32_e32 v75, 0x3f4c422a, v75
	v_add_f32_e32 v74, v74, v74
	v_add_f32_e32 v75, v75, v75
	v_mul_f32_e32 v74, 0x3fb8aa3b, v74
	v_mul_f32_e32 v75, 0x3fb8aa3b, v75
	v_exp_f32_e32 v74, v74
	v_exp_f32_e32 v75, v75
	v_pk_mul_f32 v[50:51], v[50:51], 0.5 op_sel_hi:[1,0]
	v_pk_add_f32 v[52:53], v[52:53], v[40:41]
	v_add_f32_e32 v74, 1.0, v74
	v_add_f32_e32 v75, 1.0, v75
	v_rcp_f32_e32 v74, v74
	v_rcp_f32_e32 v75, v75
	v_pk_add_f32 v[58:59], v[58:59], v[38:39]
	v_pk_add_f32 v[60:61], v[60:61], v[40:41]
	v_pk_add_f32 v[26:27], v[26:27], v[38:39]
	v_pk_fma_f32 v[74:75], v[74:75], 2.0, 1.0 op_sel_hi:[1,0,0] neg_lo:[1,0,0] neg_hi:[1,0,0]
	v_pk_add_f32 v[28:29], v[28:29], v[40:41]
	v_pk_add_f32 v[74:75], v[74:75], 1.0 op_sel_hi:[1,0]
	v_pk_add_f32 v[10:11], v[10:11], v[38:39]
	v_pk_mul_f32 v[50:51], v[50:51], v[74:75]
	v_mul_f32_e32 v74, 0x3d372713, v52
	v_mul_f32_e32 v75, 0x3d372713, v53
	v_mul_f32_e32 v74, v52, v74
	v_mul_f32_e32 v75, v53, v75
	v_fma_f32 v74, v52, v74, v52
	v_fma_f32 v75, v53, v75, v53
	v_mul_f32_e32 v74, 0x3f4c422a, v74
	v_mul_f32_e32 v75, 0x3f4c422a, v75
	v_add_f32_e32 v74, v74, v74
	v_add_f32_e32 v75, v75, v75
	v_mul_f32_e32 v74, 0x3fb8aa3b, v74
	v_mul_f32_e32 v75, 0x3fb8aa3b, v75
	v_exp_f32_e32 v74, v74
	v_exp_f32_e32 v75, v75
	v_pk_mul_f32 v[52:53], v[52:53], 0.5 op_sel_hi:[1,0]
	v_cvt_pk_bf16_f32 v50, v50, v51
	v_add_f32_e32 v74, 1.0, v74
	v_add_f32_e32 v75, 1.0, v75
	v_rcp_f32_e32 v74, v74
	v_rcp_f32_e32 v75, v75
	v_pk_add_f32 v[12:13], v[12:13], v[40:41]
	v_pk_fma_f32 v[74:75], v[74:75], 2.0, 1.0 op_sel_hi:[1,0,0] neg_lo:[1,0,0] neg_hi:[1,0,0]
	s_nop 0
	v_pk_add_f32 v[74:75], v[74:75], 1.0 op_sel_hi:[1,0]
	s_nop 0
	v_pk_mul_f32 v[52:53], v[52:53], v[74:75]
	s_nop 0
	v_cvt_pk_bf16_f32 v51, v52, v53
	global_store_dwordx2 v[72:73], v[50:51], off offset:32
	s_waitcnt vmcnt(3)
	v_mov_b64_e32 v[50:51], v[116:117]
	v_mov_b64_e32 v[52:53], v[118:119]
	v_pk_add_f32 v[46:47], v[46:47], v[50:51]
	s_nop 0
	v_mul_f32_e32 v74, 0x3d372713, v46
	v_mul_f32_e32 v75, 0x3d372713, v47
	v_mul_f32_e32 v74, v46, v74
	v_mul_f32_e32 v75, v47, v75
	v_fma_f32 v74, v46, v74, v46
	v_fma_f32 v75, v47, v75, v47
	v_mul_f32_e32 v74, 0x3f4c422a, v74
	v_mul_f32_e32 v75, 0x3f4c422a, v75
	v_add_f32_e32 v74, v74, v74
	v_add_f32_e32 v75, v75, v75
	v_mul_f32_e32 v74, 0x3fb8aa3b, v74
	v_mul_f32_e32 v75, 0x3fb8aa3b, v75
	v_exp_f32_e32 v74, v74
	v_exp_f32_e32 v75, v75
	v_pk_mul_f32 v[46:47], v[46:47], 0.5 op_sel_hi:[1,0]
	v_pk_add_f32 v[48:49], v[48:49], v[52:53]
	v_add_f32_e32 v74, 1.0, v74
	v_add_f32_e32 v75, 1.0, v75
	v_rcp_f32_e32 v74, v74
	v_rcp_f32_e32 v75, v75
	v_pk_add_f32 v[54:55], v[54:55], v[50:51]
	v_pk_add_f32 v[56:57], v[56:57], v[52:53]
	v_pk_add_f32 v[22:23], v[22:23], v[50:51]
	v_pk_fma_f32 v[74:75], v[74:75], 2.0, 1.0 op_sel_hi:[1,0,0] neg_lo:[1,0,0] neg_hi:[1,0,0]
	v_pk_add_f32 v[24:25], v[24:25], v[52:53]
	v_pk_add_f32 v[74:75], v[74:75], 1.0 op_sel_hi:[1,0]
	v_pk_add_f32 v[6:7], v[6:7], v[50:51]
	v_pk_mul_f32 v[46:47], v[46:47], v[74:75]
	v_mul_f32_e32 v74, 0x3d372713, v48
	v_mul_f32_e32 v75, 0x3d372713, v49
	v_mul_f32_e32 v74, v48, v74
	v_mul_f32_e32 v75, v49, v75
	v_fma_f32 v74, v48, v74, v48
	v_fma_f32 v75, v49, v75, v49
	v_mul_f32_e32 v74, 0x3f4c422a, v74
	v_mul_f32_e32 v75, 0x3f4c422a, v75
	v_add_f32_e32 v74, v74, v74
	v_add_f32_e32 v75, v75, v75
	v_mul_f32_e32 v74, 0x3fb8aa3b, v74
	v_mul_f32_e32 v75, 0x3fb8aa3b, v75
	v_exp_f32_e32 v74, v74
	v_exp_f32_e32 v75, v75
	v_pk_mul_f32 v[48:49], v[48:49], 0.5 op_sel_hi:[1,0]
	v_cvt_pk_bf16_f32 v46, v46, v47
	v_add_f32_e32 v74, 1.0, v74
	v_add_f32_e32 v75, 1.0, v75
	v_rcp_f32_e32 v74, v74
	v_rcp_f32_e32 v75, v75
	v_pk_add_f32 v[8:9], v[8:9], v[52:53]
	v_pk_fma_f32 v[74:75], v[74:75], 2.0, 1.0 op_sel_hi:[1,0,0] neg_lo:[1,0,0] neg_hi:[1,0,0]
	s_nop 0
	v_pk_add_f32 v[74:75], v[74:75], 1.0 op_sel_hi:[1,0]
	s_nop 0
	v_pk_mul_f32 v[48:49], v[48:49], v[74:75]
	s_nop 0
	v_cvt_pk_bf16_f32 v47, v48, v49
	global_store_dwordx2 v[72:73], v[46:47], off offset:64
	s_waitcnt vmcnt(3)
; DI int TID() { int t = threadIdx.x & 255; asm volatile("" : "+v"(t)); return t; }
; template <class E>
; DI void gemm_epi(f32x4 (&acc)[4][4], int m0, int n0, E e) {
;   const int tid_ = TID();
;   const int lane = tid_ & 63, w = tid_ >> 6;
;   const int wm = w >> 1, wn = w & 1;
; #pragma unroll
;   for (int i = 0; i < 4; ++i)
; #pragma unroll
;     for (int j = 0; j < 4; ++j) {
;       int m = m0 + wm * 64 + i * 16 + (lane & 15);
;       int n = n0 + wn * 64 + j * 16 + (lane >> 4) * 4;
;       e(m, n, acc[i][j]);
;     }
; }
; __global__ void __launch_bounds__(512, 2) mega(Params p) {
;     ...
;         gemm_epi(acc, m0, n0, [&](int m, int n, f32x4& a) {
;           float o[4];
; #pragma unroll
;           for (int j = 0; j < 4; ++j) {
;             float xv = a[j] + bs[n + j];
;             float y = 0.7978845608028654f * (xv + 0.044715f * xv * xv * xv);
;             float th = 1.f - 2.f * __builtin_amdgcn_rcpf(__expf(2.f * y) + 1.f);
;             o[j] = 0.5f * xv * (1.f + th);
;           }
;           uint2 u;
;           u.x = pack2(o[0], o[1]);
;           u.y = pack2(o[2], o[3]);
;           *(uint2*)(hd + (size_t)m * 256 + n) = u;
;         });
	v_mov_b64_e32 v[46:47], v[120:121]
	v_mov_b64_e32 v[48:49], v[122:123]
	v_pk_add_f32 v[66:67], v[66:67], v[46:47]
	s_nop 0
	v_mul_f32_e32 v71, 0x3d372713, v66
	v_mul_f32_e32 v71, v66, v71
	v_fma_f32 v71, v66, v71, v66
	v_mul_f32_e32 v71, 0x3f4c422a, v71
	v_add_f32_e32 v71, v71, v71
	v_mul_f32_e32 v71, 0x3fb8aa3b, v71
	v_exp_f32_e32 v71, v71
	v_pk_add_f32 v[68:69], v[68:69], v[48:49]
	v_pk_add_f32 v[42:43], v[42:43], v[46:47]
	v_pk_add_f32 v[44:45], v[44:45], v[48:49]
	v_add_f32_e32 v71, 1.0, v71
	v_rcp_f32_e32 v74, v71
	v_mul_f32_e32 v71, 0x3d372713, v67
	v_mul_f32_e32 v71, v67, v71
	v_fma_f32 v71, v67, v71, v67
	v_mul_f32_e32 v71, 0x3f4c422a, v71
	v_add_f32_e32 v71, v71, v71
	v_mul_f32_e32 v71, 0x3fb8aa3b, v71
	v_exp_f32_e32 v71, v71
	v_pk_mul_f32 v[66:67], v[66:67], 0.5 op_sel_hi:[1,0]
	v_pk_add_f32 v[18:19], v[18:19], v[46:47]
	v_pk_add_f32 v[20:21], v[20:21], v[48:49]
	v_add_f32_e32 v71, 1.0, v71
	v_rcp_f32_e32 v75, v71
	v_mul_f32_e32 v71, 0x3d372713, v68
	v_mul_f32_e32 v71, v68, v71
	v_fma_f32 v71, v68, v71, v68
	v_mul_f32_e32 v71, 0x3f4c422a, v71
	v_add_f32_e32 v71, v71, v71
	v_mul_f32_e32 v71, 0x3fb8aa3b, v71
	v_exp_f32_e32 v71, v71
	v_pk_fma_f32 v[74:75], v[74:75], 2.0, 1.0 op_sel_hi:[1,0,0] neg_lo:[1,0,0] neg_hi:[1,0,0]
	v_pk_add_f32 v[2:3], v[2:3], v[46:47]
	v_pk_add_f32 v[74:75], v[74:75], 1.0 op_sel_hi:[1,0]
	v_add_f32_e32 v71, 1.0, v71
	v_pk_mul_f32 v[66:67], v[66:67], v[74:75]
	v_rcp_f32_e32 v74, v71
	v_mul_f32_e32 v71, 0x3d372713, v69
	v_mul_f32_e32 v71, v69, v71
	v_fma_f32 v71, v69, v71, v69
	v_mul_f32_e32 v71, 0x3f4c422a, v71
	v_add_f32_e32 v71, v71, v71
	v_mul_f32_e32 v71, 0x3fb8aa3b, v71
	v_exp_f32_e32 v71, v71
	v_pk_mul_f32 v[68:69], v[68:69], 0.5 op_sel_hi:[1,0]
	v_cvt_pk_bf16_f32 v66, v66, v67
	v_pk_add_f32 v[4:5], v[4:5], v[48:49]
	v_add_f32_e32 v71, 1.0, v71
	v_rcp_f32_e32 v75, v71
	s_nop 0
	v_pk_fma_f32 v[74:75], v[74:75], 2.0, 1.0 op_sel_hi:[1,0,0] neg_lo:[1,0,0] neg_hi:[1,0,0]
	s_nop 0
	v_pk_add_f32 v[74:75], v[74:75], 1.0 op_sel_hi:[1,0]
	s_nop 0
	v_pk_mul_f32 v[68:69], v[68:69], v[74:75]
	s_nop 0
	v_cvt_pk_bf16_f32 v67, v68, v69
	v_mul_f32_e32 v68, 0x3d372713, v62
	v_mul_f32_e32 v69, 0x3d372713, v63
	v_mul_f32_e32 v68, v62, v68
	v_mul_f32_e32 v69, v63, v69
	v_fma_f32 v68, v62, v68, v62
	v_fma_f32 v69, v63, v69, v63
	v_mul_f32_e32 v68, 0x3f4c422a, v68
	v_mul_f32_e32 v69, 0x3f4c422a, v69
	v_add_f32_e32 v68, v68, v68
	v_add_f32_e32 v69, v69, v69
	v_mul_f32_e32 v68, 0x3fb8aa3b, v68
	v_mul_f32_e32 v69, 0x3fb8aa3b, v69
	v_exp_f32_e32 v68, v68
	v_exp_f32_e32 v69, v69
	v_pk_mul_f32 v[62:63], v[62:63], 0.5 op_sel_hi:[1,0]
	global_store_dwordx2 v[72:73], v[66:67], off offset:96
	v_add_f32_e32 v68, 1.0, v68
	v_add_f32_e32 v69, 1.0, v69
	v_rcp_f32_e32 v68, v68
	v_rcp_f32_e32 v69, v69
	v_or_b32_e32 v66, 16, v70
	v_ashrrev_i32_e32 v67, 31, v66
	v_lshlrev_b64 v[66:67], 9, v[66:67]
	v_pk_fma_f32 v[68:69], v[68:69], 2.0, 1.0 op_sel_hi:[1,0,0] neg_lo:[1,0,0] neg_hi:[1,0,0]
	s_nop 0
	v_pk_add_f32 v[68:69], v[68:69], 1.0 op_sel_hi:[1,0]
	s_nop 0
	v_pk_mul_f32 v[62:63], v[62:63], v[68:69]
	v_mul_f32_e32 v68, 0x3d372713, v64
	v_mul_f32_e32 v69, 0x3d372713, v65
	v_mul_f32_e32 v68, v64, v68
	v_mul_f32_e32 v69, v65, v69
	v_fma_f32 v68, v64, v68, v64
	v_fma_f32 v69, v65, v69, v65
	v_mul_f32_e32 v68, 0x3f4c422a, v68
	v_mul_f32_e32 v69, 0x3f4c422a, v69
	v_add_f32_e32 v68, v68, v68
	v_add_f32_e32 v69, v69, v69
	v_mul_f32_e32 v68, 0x3fb8aa3b, v68
	v_mul_f32_e32 v69, 0x3fb8aa3b, v69
	v_exp_f32_e32 v68, v68
	v_exp_f32_e32 v69, v69
	v_pk_mul_f32 v[64:65], v[64:65], 0.5 op_sel_hi:[1,0]
	v_add_f32_e32 v68, 1.0, v68
	v_add_f32_e32 v69, 1.0, v69
	v_rcp_f32_e32 v68, v68
	v_rcp_f32_e32 v69, v69
	s_nop 0
	v_pk_fma_f32 v[68:69], v[68:69], 2.0, 1.0 op_sel_hi:[1,0,0] neg_lo:[1,0,0] neg_hi:[1,0,0]
	s_nop 0
	v_pk_add_f32 v[68:69], v[68:69], 1.0 op_sel_hi:[1,0]
	s_nop 0
	v_pk_mul_f32 v[64:65], v[64:65], v[68:69]
	v_cvt_pk_bf16_f32 v68, v62, v63
	v_cvt_pk_bf16_f32 v69, v64, v65
	v_mul_f32_e32 v64, 0x3d372713, v58
	v_mul_f32_e32 v65, 0x3d372713, v59
	v_mul_f32_e32 v64, v58, v64
	v_mul_f32_e32 v65, v59, v65
	v_fma_f32 v64, v58, v64, v58
	v_fma_f32 v65, v59, v65, v59
	v_mul_f32_e32 v64, 0x3f4c422a, v64
	v_mul_f32_e32 v65, 0x3f4c422a, v65
	v_add_f32_e32 v64, v64, v64
	v_add_f32_e32 v65, v65, v65
	v_mul_f32_e32 v64, 0x3fb8aa3b, v64
	v_mul_f32_e32 v65, 0x3fb8aa3b, v65
	v_exp_f32_e32 v64, v64
	v_exp_f32_e32 v65, v65
	v_pk_mul_f32 v[58:59], v[58:59], 0.5 op_sel_hi:[1,0]
	v_lshl_add_u64 v[62:63], s[2:3], 0, v[66:67]
	v_add_f32_e32 v64, 1.0, v64
	v_add_f32_e32 v65, 1.0, v65
	v_rcp_f32_e32 v64, v64
	v_rcp_f32_e32 v65, v65
	v_lshl_add_u64 v[62:63], v[62:63], 0, v[0:1]
	global_store_dwordx2 v[62:63], v[68:69], off
	v_pk_fma_f32 v[64:65], v[64:65], 2.0, 1.0 op_sel_hi:[1,0,0] neg_lo:[1,0,0] neg_hi:[1,0,0]
	s_nop 0
	v_pk_add_f32 v[64:65], v[64:65], 1.0 op_sel_hi:[1,0]
	s_nop 0
	v_pk_mul_f32 v[58:59], v[58:59], v[64:65]
	v_mul_f32_e32 v64, 0x3d372713, v60
	v_mul_f32_e32 v65, 0x3d372713, v61
	v_mul_f32_e32 v64, v60, v64
	v_mul_f32_e32 v65, v61, v65
	v_fma_f32 v64, v60, v64, v60
	v_fma_f32 v65, v61, v65, v61
	v_mul_f32_e32 v64, 0x3f4c422a, v64
	v_mul_f32_e32 v65, 0x3f4c422a, v65
	v_add_f32_e32 v64, v64, v64
	v_add_f32_e32 v65, v65, v65
	v_mul_f32_e32 v64, 0x3fb8aa3b, v64
	v_mul_f32_e32 v65, 0x3fb8aa3b, v65
	v_exp_f32_e32 v64, v64
	v_exp_f32_e32 v65, v65
	v_pk_mul_f32 v[60:61], v[60:61], 0.5 op_sel_hi:[1,0]
	v_cvt_pk_bf16_f32 v58, v58, v59
	v_add_f32_e32 v64, 1.0, v64
	v_add_f32_e32 v65, 1.0, v65
	v_rcp_f32_e32 v64, v64
	v_rcp_f32_e32 v65, v65
	s_nop 0
	v_pk_fma_f32 v[64:65], v[64:65], 2.0, 1.0 op_sel_hi:[1,0,0] neg_lo:[1,0,0] neg_hi:[1,0,0]
	s_nop 0
; DI int TID() { int t = threadIdx.x & 255; asm volatile("" : "+v"(t)); return t; }
; template <class E>
; DI void gemm_epi(f32x4 (&acc)[4][4], int m0, int n0, E e) {
;   const int tid_ = TID();
;   const int lane = tid_ & 63, w = tid_ >> 6;
;   const int wm = w >> 1, wn = w & 1;
; #pragma unroll
;   for (int i = 0; i < 4; ++i)
; #pragma unroll
;     for (int j = 0; j < 4; ++j) {
;       int m = m0 + wm * 64 + i * 16 + (lane & 15);
;       int n = n0 + wn * 64 + j * 16 + (lane >> 4) * 4;
;       e(m, n, acc[i][j]);
;     }
; }
; __global__ void __launch_bounds__(512, 2) mega(Params p) {
;     ...
;         gemm_epi(acc, m0, n0, [&](int m, int n, f32x4& a) {
;           float o[4];
; #pragma unroll
;           for (int j = 0; j < 4; ++j) {
;             float xv = a[j] + bs[n + j];
;             float y = 0.7978845608028654f * (xv + 0.044715f * xv * xv * xv);
;             float th = 1.f - 2.f * __builtin_amdgcn_rcpf(__expf(2.f * y) + 1.f);
;             o[j] = 0.5f * xv * (1.f + th);
;           }
;           uint2 u;
;           u.x = pack2(o[0], o[1]);
;           u.y = pack2(o[2], o[3]);
;           *(uint2*)(hd + (size_t)m * 256 + n) = u;
;         });
	v_pk_add_f32 v[64:65], v[64:65], 1.0 op_sel_hi:[1,0]
	s_nop 0
	v_pk_mul_f32 v[60:61], v[60:61], v[64:65]
	s_nop 0
	v_cvt_pk_bf16_f32 v59, v60, v61
	global_store_dwordx2 v[62:63], v[58:59], off offset:32
	v_mul_f32_e32 v58, 0x3d372713, v54
	v_mul_f32_e32 v59, 0x3d372713, v55
	v_mul_f32_e32 v58, v54, v58
	v_mul_f32_e32 v59, v55, v59
	v_fma_f32 v58, v54, v58, v54
	v_fma_f32 v59, v55, v59, v55
	v_mul_f32_e32 v58, 0x3f4c422a, v58
	v_mul_f32_e32 v59, 0x3f4c422a, v59
	v_add_f32_e32 v58, v58, v58
	v_add_f32_e32 v59, v59, v59
	v_mul_f32_e32 v58, 0x3fb8aa3b, v58
	v_mul_f32_e32 v59, 0x3fb8aa3b, v59
	v_exp_f32_e32 v58, v58
	v_exp_f32_e32 v59, v59
	v_pk_mul_f32 v[54:55], v[54:55], 0.5 op_sel_hi:[1,0]
	v_add_f32_e32 v58, 1.0, v58
	v_add_f32_e32 v59, 1.0, v59
	v_rcp_f32_e32 v58, v58
	v_rcp_f32_e32 v59, v59
	s_nop 0
	v_pk_fma_f32 v[58:59], v[58:59], 2.0, 1.0 op_sel_hi:[1,0,0] neg_lo:[1,0,0] neg_hi:[1,0,0]
	s_nop 0
	v_pk_add_f32 v[58:59], v[58:59], 1.0 op_sel_hi:[1,0]
	s_nop 0
	v_pk_mul_f32 v[54:55], v[54:55], v[58:59]
	v_mul_f32_e32 v58, 0x3d372713, v56
	v_mul_f32_e32 v59, 0x3d372713, v57
	v_mul_f32_e32 v58, v56, v58
	v_mul_f32_e32 v59, v57, v59
	v_fma_f32 v58, v56, v58, v56
	v_fma_f32 v59, v57, v59, v57
	v_mul_f32_e32 v58, 0x3f4c422a, v58
	v_mul_f32_e32 v59, 0x3f4c422a, v59
	v_add_f32_e32 v58, v58, v58
	v_add_f32_e32 v59, v59, v59
	v_mul_f32_e32 v58, 0x3fb8aa3b, v58
	v_mul_f32_e32 v59, 0x3fb8aa3b, v59
	v_exp_f32_e32 v58, v58
	v_exp_f32_e32 v59, v59
	v_pk_mul_f32 v[56:57], v[56:57], 0.5 op_sel_hi:[1,0]
	v_cvt_pk_bf16_f32 v54, v54, v55
	v_add_f32_e32 v58, 1.0, v58
	v_add_f32_e32 v59, 1.0, v59
	v_rcp_f32_e32 v58, v58
	v_rcp_f32_e32 v59, v59
	s_nop 0
	v_pk_fma_f32 v[58:59], v[58:59], 2.0, 1.0 op_sel_hi:[1,0,0] neg_lo:[1,0,0] neg_hi:[1,0,0]
	s_nop 0
	v_pk_add_f32 v[58:59], v[58:59], 1.0 op_sel_hi:[1,0]
	s_nop 0
	v_pk_mul_f32 v[56:57], v[56:57], v[58:59]
	s_nop 0
	v_cvt_pk_bf16_f32 v55, v56, v57
	global_store_dwordx2 v[62:63], v[54:55], off offset:64
	v_mul_f32_e32 v54, 0x3d372713, v42
	v_mul_f32_e32 v55, 0x3d372713, v43
	v_mul_f32_e32 v54, v42, v54
	v_mul_f32_e32 v55, v43, v55
	v_fma_f32 v54, v42, v54, v42
	v_fma_f32 v55, v43, v55, v43
	v_mul_f32_e32 v54, 0x3f4c422a, v54
	v_mul_f32_e32 v55, 0x3f4c422a, v55
	v_add_f32_e32 v54, v54, v54
	v_add_f32_e32 v55, v55, v55
	v_mul_f32_e32 v54, 0x3fb8aa3b, v54
	v_mul_f32_e32 v55, 0x3fb8aa3b, v55
	v_exp_f32_e32 v54, v54
	v_exp_f32_e32 v55, v55
	v_pk_mul_f32 v[42:43], v[42:43], 0.5 op_sel_hi:[1,0]
	v_add_f32_e32 v54, 1.0, v54
	v_add_f32_e32 v55, 1.0, v55
	v_rcp_f32_e32 v54, v54
	v_rcp_f32_e32 v55, v55
	s_nop 0
	v_pk_fma_f32 v[54:55], v[54:55], 2.0, 1.0 op_sel_hi:[1,0,0] neg_lo:[1,0,0] neg_hi:[1,0,0]
	s_nop 0
	v_pk_add_f32 v[54:55], v[54:55], 1.0 op_sel_hi:[1,0]
	s_nop 0
	v_pk_mul_f32 v[42:43], v[42:43], v[54:55]
	v_mul_f32_e32 v54, 0x3d372713, v44
	v_mul_f32_e32 v55, 0x3d372713, v45
	v_mul_f32_e32 v54, v44, v54
	v_mul_f32_e32 v55, v45, v55
	v_fma_f32 v54, v44, v54, v44
	v_fma_f32 v55, v45, v55, v45
	v_mul_f32_e32 v54, 0x3f4c422a, v54
	v_mul_f32_e32 v55, 0x3f4c422a, v55
	v_add_f32_e32 v54, v54, v54
	v_add_f32_e32 v55, v55, v55
	v_mul_f32_e32 v54, 0x3fb8aa3b, v54
	v_mul_f32_e32 v55, 0x3fb8aa3b, v55
	v_exp_f32_e32 v54, v54
	v_exp_f32_e32 v55, v55
	v_pk_mul_f32 v[44:45], v[44:45], 0.5 op_sel_hi:[1,0]
	v_cvt_pk_bf16_f32 v42, v42, v43
	v_add_f32_e32 v54, 1.0, v54
	v_add_f32_e32 v55, 1.0, v55
	v_rcp_f32_e32 v54, v54
	v_rcp_f32_e32 v55, v55
	s_nop 0
	v_pk_fma_f32 v[54:55], v[54:55], 2.0, 1.0 op_sel_hi:[1,0,0] neg_lo:[1,0,0] neg_hi:[1,0,0]
	s_nop 0
	v_pk_add_f32 v[54:55], v[54:55], 1.0 op_sel_hi:[1,0]
	s_nop 0
	v_pk_mul_f32 v[44:45], v[44:45], v[54:55]
	s_nop 0
	v_cvt_pk_bf16_f32 v43, v44, v45
	v_mul_f32_e32 v44, 0x3d372713, v34
	v_mul_f32_e32 v45, 0x3d372713, v35
	v_mul_f32_e32 v44, v34, v44
	v_mul_f32_e32 v45, v35, v45
	v_fma_f32 v44, v34, v44, v34
	v_fma_f32 v45, v35, v45, v35
	v_mul_f32_e32 v44, 0x3f4c422a, v44
	v_mul_f32_e32 v45, 0x3f4c422a, v45
	v_add_f32_e32 v44, v44, v44
	v_add_f32_e32 v45, v45, v45
	v_mul_f32_e32 v44, 0x3fb8aa3b, v44
	v_mul_f32_e32 v45, 0x3fb8aa3b, v45
	v_exp_f32_e32 v44, v44
	v_exp_f32_e32 v45, v45
	v_pk_mul_f32 v[34:35], v[34:35], 0.5 op_sel_hi:[1,0]
	global_store_dwordx2 v[62:63], v[42:43], off offset:96
	v_add_f32_e32 v44, 1.0, v44
	v_add_f32_e32 v45, 1.0, v45
	v_rcp_f32_e32 v44, v44
	v_rcp_f32_e32 v45, v45
	v_or_b32_e32 v42, 32, v70
	v_ashrrev_i32_e32 v43, 31, v42
	v_lshlrev_b64 v[42:43], 9, v[42:43]
	v_pk_fma_f32 v[44:45], v[44:45], 2.0, 1.0 op_sel_hi:[1,0,0] neg_lo:[1,0,0] neg_hi:[1,0,0]
	s_nop 0
	v_pk_add_f32 v[44:45], v[44:45], 1.0 op_sel_hi:[1,0]
	s_nop 0
	v_pk_mul_f32 v[34:35], v[34:35], v[44:45]
	v_mul_f32_e32 v44, 0x3d372713, v36
	v_mul_f32_e32 v45, 0x3d372713, v37
	v_mul_f32_e32 v44, v36, v44
	v_mul_f32_e32 v45, v37, v45
	v_fma_f32 v44, v36, v44, v36
	v_fma_f32 v45, v37, v45, v37
	v_mul_f32_e32 v44, 0x3f4c422a, v44
	v_mul_f32_e32 v45, 0x3f4c422a, v45
	v_add_f32_e32 v44, v44, v44
	v_add_f32_e32 v45, v45, v45
	v_mul_f32_e32 v44, 0x3fb8aa3b, v44
	v_mul_f32_e32 v45, 0x3fb8aa3b, v45
	v_exp_f32_e32 v44, v44
	v_exp_f32_e32 v45, v45
	v_pk_mul_f32 v[36:37], v[36:37], 0.5 op_sel_hi:[1,0]
	v_add_f32_e32 v44, 1.0, v44
	v_add_f32_e32 v45, 1.0, v45
	v_rcp_f32_e32 v44, v44
	v_rcp_f32_e32 v45, v45
	s_nop 0
	v_pk_fma_f32 v[44:45], v[44:45], 2.0, 1.0 op_sel_hi:[1,0,0] neg_lo:[1,0,0] neg_hi:[1,0,0]
	s_nop 0
	v_pk_add_f32 v[44:45], v[44:45], 1.0 op_sel_hi:[1,0]
	s_nop 0
	v_pk_mul_f32 v[36:37], v[36:37], v[44:45]
	v_cvt_pk_bf16_f32 v44, v34, v35
	v_cvt_pk_bf16_f32 v45, v36, v37
	v_mul_f32_e32 v36, 0x3d372713, v26
	v_mul_f32_e32 v37, 0x3d372713, v27
	v_mul_f32_e32 v36, v26, v36
	v_mul_f32_e32 v37, v27, v37
; DI int TID() { int t = threadIdx.x & 255; asm volatile("" : "+v"(t)); return t; }
; template <class E>
; DI void gemm_epi(f32x4 (&acc)[4][4], int m0, int n0, E e) {
;   const int tid_ = TID();
;   const int lane = tid_ & 63, w = tid_ >> 6;
;   const int wm = w >> 1, wn = w & 1;
; #pragma unroll
;   for (int i = 0; i < 4; ++i)
; #pragma unroll
;     for (int j = 0; j < 4; ++j) {
;       int m = m0 + wm * 64 + i * 16 + (lane & 15);
;       int n = n0 + wn * 64 + j * 16 + (lane >> 4) * 4;
;       e(m, n, acc[i][j]);
;     }
; }
; __global__ void __launch_bounds__(512, 2) mega(Params p) {
;     ...
;         gemm_epi(acc, m0, n0, [&](int m, int n, f32x4& a) {
;           float o[4];
; #pragma unroll
;           for (int j = 0; j < 4; ++j) {
;             float xv = a[j] + bs[n + j];
;             float y = 0.7978845608028654f * (xv + 0.044715f * xv * xv * xv);
;             float th = 1.f - 2.f * __builtin_amdgcn_rcpf(__expf(2.f * y) + 1.f);
;             o[j] = 0.5f * xv * (1.f + th);
;           }
;           uint2 u;
;           u.x = pack2(o[0], o[1]);
;           u.y = pack2(o[2], o[3]);
;           *(uint2*)(hd + (size_t)m * 256 + n) = u;
;         });
	v_fma_f32 v36, v26, v36, v26
	v_fma_f32 v37, v27, v37, v27
	v_mul_f32_e32 v36, 0x3f4c422a, v36
	v_mul_f32_e32 v37, 0x3f4c422a, v37
	v_add_f32_e32 v36, v36, v36
	v_add_f32_e32 v37, v37, v37
	v_mul_f32_e32 v36, 0x3fb8aa3b, v36
	v_mul_f32_e32 v37, 0x3fb8aa3b, v37
	v_exp_f32_e32 v36, v36
	v_exp_f32_e32 v37, v37
	v_pk_mul_f32 v[26:27], v[26:27], 0.5 op_sel_hi:[1,0]
	v_lshl_add_u64 v[34:35], s[2:3], 0, v[42:43]
	v_add_f32_e32 v36, 1.0, v36
	v_add_f32_e32 v37, 1.0, v37
	v_rcp_f32_e32 v36, v36
	v_rcp_f32_e32 v37, v37
	v_lshl_add_u64 v[34:35], v[34:35], 0, v[0:1]
	global_store_dwordx2 v[34:35], v[44:45], off
	v_pk_fma_f32 v[36:37], v[36:37], 2.0, 1.0 op_sel_hi:[1,0,0] neg_lo:[1,0,0] neg_hi:[1,0,0]
	s_nop 0
	v_pk_add_f32 v[36:37], v[36:37], 1.0 op_sel_hi:[1,0]
	s_nop 0
	v_pk_mul_f32 v[26:27], v[26:27], v[36:37]
	v_mul_f32_e32 v36, 0x3d372713, v28
	v_mul_f32_e32 v37, 0x3d372713, v29
	v_mul_f32_e32 v36, v28, v36
	v_mul_f32_e32 v37, v29, v37
	v_fma_f32 v36, v28, v36, v28
	v_fma_f32 v37, v29, v37, v29
	v_mul_f32_e32 v36, 0x3f4c422a, v36
	v_mul_f32_e32 v37, 0x3f4c422a, v37
	v_add_f32_e32 v36, v36, v36
	v_add_f32_e32 v37, v37, v37
	v_mul_f32_e32 v36, 0x3fb8aa3b, v36
	v_mul_f32_e32 v37, 0x3fb8aa3b, v37
	v_exp_f32_e32 v36, v36
	v_exp_f32_e32 v37, v37
	v_pk_mul_f32 v[28:29], v[28:29], 0.5 op_sel_hi:[1,0]
	v_cvt_pk_bf16_f32 v26, v26, v27
	v_add_f32_e32 v36, 1.0, v36
	v_add_f32_e32 v37, 1.0, v37
	v_rcp_f32_e32 v36, v36
	v_rcp_f32_e32 v37, v37
	s_nop 0
	v_pk_fma_f32 v[36:37], v[36:37], 2.0, 1.0 op_sel_hi:[1,0,0] neg_lo:[1,0,0] neg_hi:[1,0,0]
	s_nop 0
	v_pk_add_f32 v[36:37], v[36:37], 1.0 op_sel_hi:[1,0]
	s_nop 0
	v_pk_mul_f32 v[28:29], v[28:29], v[36:37]
	s_nop 0
	v_cvt_pk_bf16_f32 v27, v28, v29
	global_store_dwordx2 v[34:35], v[26:27], off offset:32
	v_mul_f32_e32 v26, 0x3d372713, v22
	v_mul_f32_e32 v27, 0x3d372713, v23
	v_mul_f32_e32 v26, v22, v26
	v_mul_f32_e32 v27, v23, v27
	v_fma_f32 v26, v22, v26, v22
	v_fma_f32 v27, v23, v27, v23
	v_mul_f32_e32 v26, 0x3f4c422a, v26
	v_mul_f32_e32 v27, 0x3f4c422a, v27
	v_add_f32_e32 v26, v26, v26
	v_add_f32_e32 v27, v27, v27
	v_mul_f32_e32 v26, 0x3fb8aa3b, v26
	v_mul_f32_e32 v27, 0x3fb8aa3b, v27
	v_exp_f32_e32 v26, v26
	v_exp_f32_e32 v27, v27
	v_pk_mul_f32 v[22:23], v[22:23], 0.5 op_sel_hi:[1,0]
	v_add_f32_e32 v26, 1.0, v26
	v_add_f32_e32 v27, 1.0, v27
	v_rcp_f32_e32 v26, v26
	v_rcp_f32_e32 v27, v27
	s_nop 0
	v_pk_fma_f32 v[26:27], v[26:27], 2.0, 1.0 op_sel_hi:[1,0,0] neg_lo:[1,0,0] neg_hi:[1,0,0]
	s_nop 0
	v_pk_add_f32 v[26:27], v[26:27], 1.0 op_sel_hi:[1,0]
	s_nop 0
	v_pk_mul_f32 v[22:23], v[22:23], v[26:27]
	v_mul_f32_e32 v26, 0x3d372713, v24
	v_mul_f32_e32 v27, 0x3d372713, v25
	v_mul_f32_e32 v26, v24, v26
	v_mul_f32_e32 v27, v25, v27
	v_fma_f32 v26, v24, v26, v24
	v_fma_f32 v27, v25, v27, v25
	v_mul_f32_e32 v26, 0x3f4c422a, v26
	v_mul_f32_e32 v27, 0x3f4c422a, v27
	v_add_f32_e32 v26, v26, v26
	v_add_f32_e32 v27, v27, v27
	v_mul_f32_e32 v26, 0x3fb8aa3b, v26
	v_mul_f32_e32 v27, 0x3fb8aa3b, v27
	v_exp_f32_e32 v26, v26
	v_exp_f32_e32 v27, v27
	v_pk_mul_f32 v[24:25], v[24:25], 0.5 op_sel_hi:[1,0]
	v_cvt_pk_bf16_f32 v22, v22, v23
	v_add_f32_e32 v26, 1.0, v26
	v_add_f32_e32 v27, 1.0, v27
	v_rcp_f32_e32 v26, v26
	v_rcp_f32_e32 v27, v27
	s_nop 0
	v_pk_fma_f32 v[26:27], v[26:27], 2.0, 1.0 op_sel_hi:[1,0,0] neg_lo:[1,0,0] neg_hi:[1,0,0]
	s_nop 0
	v_pk_add_f32 v[26:27], v[26:27], 1.0 op_sel_hi:[1,0]
	s_nop 0
	v_pk_mul_f32 v[24:25], v[24:25], v[26:27]
	s_nop 0
	v_cvt_pk_bf16_f32 v23, v24, v25
	global_store_dwordx2 v[34:35], v[22:23], off offset:64
	v_mul_f32_e32 v22, 0x3d372713, v18
	v_mul_f32_e32 v23, 0x3d372713, v19
	v_mul_f32_e32 v22, v18, v22
	v_mul_f32_e32 v23, v19, v23
	v_fma_f32 v22, v18, v22, v18
	v_fma_f32 v23, v19, v23, v19
	v_mul_f32_e32 v22, 0x3f4c422a, v22
	v_mul_f32_e32 v23, 0x3f4c422a, v23
	v_add_f32_e32 v22, v22, v22
	v_add_f32_e32 v23, v23, v23
	v_mul_f32_e32 v22, 0x3fb8aa3b, v22
	v_mul_f32_e32 v23, 0x3fb8aa3b, v23
	v_exp_f32_e32 v22, v22
	v_exp_f32_e32 v23, v23
	v_pk_mul_f32 v[18:19], v[18:19], 0.5 op_sel_hi:[1,0]
	v_add_f32_e32 v22, 1.0, v22
	v_add_f32_e32 v23, 1.0, v23
	v_rcp_f32_e32 v22, v22
	v_rcp_f32_e32 v23, v23
	s_nop 0
	v_pk_fma_f32 v[22:23], v[22:23], 2.0, 1.0 op_sel_hi:[1,0,0] neg_lo:[1,0,0] neg_hi:[1,0,0]
	s_nop 0
	v_pk_add_f32 v[22:23], v[22:23], 1.0 op_sel_hi:[1,0]
	s_nop 0
	v_pk_mul_f32 v[18:19], v[18:19], v[22:23]
	v_mul_f32_e32 v22, 0x3d372713, v20
	v_mul_f32_e32 v23, 0x3d372713, v21
	v_mul_f32_e32 v22, v20, v22
	v_mul_f32_e32 v23, v21, v23
	v_fma_f32 v22, v20, v22, v20
	v_fma_f32 v23, v21, v23, v21
	v_mul_f32_e32 v22, 0x3f4c422a, v22
	v_mul_f32_e32 v23, 0x3f4c422a, v23
	v_add_f32_e32 v22, v22, v22
	v_add_f32_e32 v23, v23, v23
	v_mul_f32_e32 v22, 0x3fb8aa3b, v22
	v_mul_f32_e32 v23, 0x3fb8aa3b, v23
	v_exp_f32_e32 v22, v22
	v_exp_f32_e32 v23, v23
	v_pk_mul_f32 v[20:21], v[20:21], 0.5 op_sel_hi:[1,0]
	v_cvt_pk_bf16_f32 v18, v18, v19
	v_add_f32_e32 v22, 1.0, v22
	v_add_f32_e32 v23, 1.0, v23
	v_rcp_f32_e32 v22, v22
	v_rcp_f32_e32 v23, v23
	s_nop 0
	v_pk_fma_f32 v[22:23], v[22:23], 2.0, 1.0 op_sel_hi:[1,0,0] neg_lo:[1,0,0] neg_hi:[1,0,0]
	s_nop 0
	v_pk_add_f32 v[22:23], v[22:23], 1.0 op_sel_hi:[1,0]
	s_nop 0
	v_pk_mul_f32 v[20:21], v[20:21], v[22:23]
	s_nop 0
	v_cvt_pk_bf16_f32 v19, v20, v21
	v_mul_f32_e32 v20, 0x3d372713, v14
	v_mul_f32_e32 v21, 0x3d372713, v15
	v_mul_f32_e32 v20, v14, v20
	v_mul_f32_e32 v21, v15, v21
	v_fma_f32 v20, v14, v20, v14
	v_fma_f32 v21, v15, v21, v15
	v_mul_f32_e32 v20, 0x3f4c422a, v20
	v_mul_f32_e32 v21, 0x3f4c422a, v21
	v_add_f32_e32 v20, v20, v20
	v_add_f32_e32 v21, v21, v21
	v_mul_f32_e32 v20, 0x3fb8aa3b, v20
	v_mul_f32_e32 v21, 0x3fb8aa3b, v21
	v_exp_f32_e32 v20, v20
; DI int TID() { int t = threadIdx.x & 255; asm volatile("" : "+v"(t)); return t; }
; template <class E>
; DI void gemm_epi(f32x4 (&acc)[4][4], int m0, int n0, E e) {
;   const int tid_ = TID();
;   const int lane = tid_ & 63, w = tid_ >> 6;
;   const int wm = w >> 1, wn = w & 1;
; #pragma unroll
;   for (int i = 0; i < 4; ++i)
; #pragma unroll
;     for (int j = 0; j < 4; ++j) {
;       int m = m0 + wm * 64 + i * 16 + (lane & 15);
;       int n = n0 + wn * 64 + j * 16 + (lane >> 4) * 4;
;       e(m, n, acc[i][j]);
;     }
; }
; __global__ void __launch_bounds__(512, 2) mega(Params p) {
;     ...
;         gemm_epi(acc, m0, n0, [&](int m, int n, f32x4& a) {
;           float o[4];
; #pragma unroll
;           for (int j = 0; j < 4; ++j) {
;             float xv = a[j] + bs[n + j];
;             float y = 0.7978845608028654f * (xv + 0.044715f * xv * xv * xv);
;             float th = 1.f - 2.f * __builtin_amdgcn_rcpf(__expf(2.f * y) + 1.f);
;             o[j] = 0.5f * xv * (1.f + th);
;           }
;           uint2 u;
;           u.x = pack2(o[0], o[1]);
;           u.y = pack2(o[2], o[3]);
;           *(uint2*)(hd + (size_t)m * 256 + n) = u;
;         });
	v_exp_f32_e32 v21, v21
	v_pk_mul_f32 v[14:15], v[14:15], 0.5 op_sel_hi:[1,0]
	global_store_dwordx2 v[34:35], v[18:19], off offset:96
	v_add_f32_e32 v20, 1.0, v20
	v_add_f32_e32 v21, 1.0, v21
	v_rcp_f32_e32 v20, v20
	v_rcp_f32_e32 v21, v21
	v_or_b32_e32 v18, 48, v70
	v_ashrrev_i32_e32 v19, 31, v18
	v_lshlrev_b64 v[18:19], 9, v[18:19]
	v_pk_fma_f32 v[20:21], v[20:21], 2.0, 1.0 op_sel_hi:[1,0,0] neg_lo:[1,0,0] neg_hi:[1,0,0]
	s_nop 0
	v_pk_add_f32 v[20:21], v[20:21], 1.0 op_sel_hi:[1,0]
	s_nop 0
	v_pk_mul_f32 v[14:15], v[14:15], v[20:21]
	v_mul_f32_e32 v20, 0x3d372713, v16
	v_mul_f32_e32 v21, 0x3d372713, v17
	v_mul_f32_e32 v20, v16, v20
	v_mul_f32_e32 v21, v17, v21
	v_fma_f32 v20, v16, v20, v16
	v_fma_f32 v21, v17, v21, v17
	v_mul_f32_e32 v20, 0x3f4c422a, v20
	v_mul_f32_e32 v21, 0x3f4c422a, v21
	v_add_f32_e32 v20, v20, v20
	v_add_f32_e32 v21, v21, v21
	v_mul_f32_e32 v20, 0x3fb8aa3b, v20
	v_mul_f32_e32 v21, 0x3fb8aa3b, v21
	v_exp_f32_e32 v20, v20
	v_exp_f32_e32 v21, v21
	v_pk_mul_f32 v[16:17], v[16:17], 0.5 op_sel_hi:[1,0]
	v_add_f32_e32 v20, 1.0, v20
	v_add_f32_e32 v21, 1.0, v21
	v_rcp_f32_e32 v20, v20
	v_rcp_f32_e32 v21, v21
	s_nop 0
	v_pk_fma_f32 v[20:21], v[20:21], 2.0, 1.0 op_sel_hi:[1,0,0] neg_lo:[1,0,0] neg_hi:[1,0,0]
	s_nop 0
	v_pk_add_f32 v[20:21], v[20:21], 1.0 op_sel_hi:[1,0]
	s_nop 0
	v_pk_mul_f32 v[16:17], v[16:17], v[20:21]
	v_cvt_pk_bf16_f32 v20, v14, v15
	v_lshl_add_u64 v[14:15], s[2:3], 0, v[18:19]
	v_lshl_add_u64 v[14:15], v[14:15], 0, v[0:1]
	v_mul_f32_e32 v0, 0x3d372713, v10
	v_mul_f32_e32 v0, v10, v0
	v_fma_f32 v0, v10, v0, v10
	v_mul_f32_e32 v0, 0x3f4c422a, v0
	v_add_f32_e32 v0, v0, v0
	v_mul_f32_e32 v0, 0x3fb8aa3b, v0
	v_exp_f32_e32 v0, v0
	v_cvt_pk_bf16_f32 v21, v16, v17
	global_store_dwordx2 v[14:15], v[20:21], off
	v_add_f32_e32 v0, 1.0, v0
	v_rcp_f32_e32 v16, v0
	v_mul_f32_e32 v0, 0x3d372713, v11
	v_mul_f32_e32 v0, v11, v0
	v_fma_f32 v0, v11, v0, v11
	v_mul_f32_e32 v0, 0x3f4c422a, v0
	v_add_f32_e32 v0, v0, v0
	v_mul_f32_e32 v0, 0x3fb8aa3b, v0
	v_exp_f32_e32 v0, v0
	v_pk_mul_f32 v[10:11], v[10:11], 0.5 op_sel_hi:[1,0]
	v_add_f32_e32 v0, 1.0, v0
	v_rcp_f32_e32 v17, v0
	v_mul_f32_e32 v0, 0x3d372713, v12
	v_mul_f32_e32 v0, v12, v0
	v_fma_f32 v0, v12, v0, v12
	v_mul_f32_e32 v0, 0x3f4c422a, v0
	v_add_f32_e32 v0, v0, v0
	v_mul_f32_e32 v0, 0x3fb8aa3b, v0
	v_exp_f32_e32 v0, v0
	v_pk_fma_f32 v[16:17], v[16:17], 2.0, 1.0 op_sel_hi:[1,0,0] neg_lo:[1,0,0] neg_hi:[1,0,0]
	v_add_f32_e32 v0, 1.0, v0
	v_pk_add_f32 v[16:17], v[16:17], 1.0 op_sel_hi:[1,0]
	s_nop 0
	v_pk_mul_f32 v[10:11], v[10:11], v[16:17]
	v_rcp_f32_e32 v16, v0
	v_mul_f32_e32 v0, 0x3d372713, v13
	v_mul_f32_e32 v0, v13, v0
	v_fma_f32 v0, v13, v0, v13
	v_mul_f32_e32 v0, 0x3f4c422a, v0
	v_add_f32_e32 v0, v0, v0
	v_mul_f32_e32 v0, 0x3fb8aa3b, v0
	v_exp_f32_e32 v0, v0
	v_pk_mul_f32 v[12:13], v[12:13], 0.5 op_sel_hi:[1,0]
	v_cvt_pk_bf16_f32 v10, v10, v11
	v_add_f32_e32 v0, 1.0, v0
	v_rcp_f32_e32 v17, v0
	v_mul_f32_e32 v0, 0x3d372713, v6
	v_mul_f32_e32 v0, v6, v0
	v_fma_f32 v0, v6, v0, v6
	v_mul_f32_e32 v0, 0x3f4c422a, v0
	v_add_f32_e32 v0, v0, v0
	v_mul_f32_e32 v0, 0x3fb8aa3b, v0
	v_exp_f32_e32 v0, v0
	v_pk_fma_f32 v[16:17], v[16:17], 2.0, 1.0 op_sel_hi:[1,0,0] neg_lo:[1,0,0] neg_hi:[1,0,0]
	v_add_f32_e32 v0, 1.0, v0
	v_pk_add_f32 v[16:17], v[16:17], 1.0 op_sel_hi:[1,0]
	s_nop 0
	v_pk_mul_f32 v[12:13], v[12:13], v[16:17]
	s_nop 0
	v_cvt_pk_bf16_f32 v11, v12, v13
	global_store_dwordx2 v[14:15], v[10:11], off offset:32
	v_rcp_f32_e32 v10, v0
	v_mul_f32_e32 v0, 0x3d372713, v7
	v_mul_f32_e32 v0, v7, v0
	v_fma_f32 v0, v7, v0, v7
	v_mul_f32_e32 v0, 0x3f4c422a, v0
	v_add_f32_e32 v0, v0, v0
	v_mul_f32_e32 v0, 0x3fb8aa3b, v0
	v_exp_f32_e32 v0, v0
	v_pk_mul_f32 v[6:7], v[6:7], 0.5 op_sel_hi:[1,0]
	v_add_f32_e32 v0, 1.0, v0
	v_rcp_f32_e32 v11, v0
	v_mul_f32_e32 v0, 0x3d372713, v8
	v_mul_f32_e32 v0, v8, v0
	v_fma_f32 v0, v8, v0, v8
	v_mul_f32_e32 v0, 0x3f4c422a, v0
	v_add_f32_e32 v0, v0, v0
	v_mul_f32_e32 v0, 0x3fb8aa3b, v0
	v_exp_f32_e32 v0, v0
	v_pk_fma_f32 v[10:11], v[10:11], 2.0, 1.0 op_sel_hi:[1,0,0] neg_lo:[1,0,0] neg_hi:[1,0,0]
	v_add_f32_e32 v0, 1.0, v0
	v_pk_add_f32 v[10:11], v[10:11], 1.0 op_sel_hi:[1,0]
	s_nop 0
	v_pk_mul_f32 v[6:7], v[6:7], v[10:11]
	v_rcp_f32_e32 v10, v0
	v_mul_f32_e32 v0, 0x3d372713, v9
	v_mul_f32_e32 v0, v9, v0
	v_fma_f32 v0, v9, v0, v9
	v_mul_f32_e32 v0, 0x3f4c422a, v0
	v_add_f32_e32 v0, v0, v0
	v_mul_f32_e32 v0, 0x3fb8aa3b, v0
	v_exp_f32_e32 v0, v0
	v_pk_mul_f32 v[8:9], v[8:9], 0.5 op_sel_hi:[1,0]
	v_cvt_pk_bf16_f32 v6, v6, v7
	v_add_f32_e32 v0, 1.0, v0
	v_rcp_f32_e32 v11, v0
	v_mul_f32_e32 v0, 0x3d372713, v2
	v_mul_f32_e32 v0, v2, v0
	v_fma_f32 v0, v2, v0, v2
	v_mul_f32_e32 v0, 0x3f4c422a, v0
	v_add_f32_e32 v0, v0, v0
	v_mul_f32_e32 v0, 0x3fb8aa3b, v0
	v_exp_f32_e32 v0, v0
	v_pk_fma_f32 v[10:11], v[10:11], 2.0, 1.0 op_sel_hi:[1,0,0] neg_lo:[1,0,0] neg_hi:[1,0,0]
	v_add_f32_e32 v0, 1.0, v0
	v_pk_add_f32 v[10:11], v[10:11], 1.0 op_sel_hi:[1,0]
	s_nop 0
	v_pk_mul_f32 v[8:9], v[8:9], v[10:11]
	s_nop 0
	v_cvt_pk_bf16_f32 v7, v8, v9
	global_store_dwordx2 v[14:15], v[6:7], off offset:64
	v_rcp_f32_e32 v6, v0
	v_mul_f32_e32 v0, 0x3d372713, v3
	v_mul_f32_e32 v0, v3, v0
	v_fma_f32 v0, v3, v0, v3
	v_mul_f32_e32 v0, 0x3f4c422a, v0
	v_add_f32_e32 v0, v0, v0
	v_mul_f32_e32 v0, 0x3fb8aa3b, v0
	v_exp_f32_e32 v0, v0
	v_pk_mul_f32 v[2:3], v[2:3], 0.5 op_sel_hi:[1,0]
	v_add_f32_e32 v0, 1.0, v0
	v_rcp_f32_e32 v7, v0
	v_mul_f32_e32 v0, 0x3d372713, v4
	v_mul_f32_e32 v0, v4, v0
	v_fma_f32 v0, v4, v0, v4
	v_mul_f32_e32 v0, 0x3f4c422a, v0
	v_add_f32_e32 v0, v0, v0
	v_mul_f32_e32 v0, 0x3fb8aa3b, v0
	v_exp_f32_e32 v0, v0
	v_pk_fma_f32 v[6:7], v[6:7], 2.0, 1.0 op_sel_hi:[1,0,0] neg_lo:[1,0,0] neg_hi:[1,0,0]
	v_add_f32_e32 v0, 1.0, v0
	v_pk_add_f32 v[6:7], v[6:7], 1.0 op_sel_hi:[1,0]
	s_nop 0
	v_pk_mul_f32 v[2:3], v[2:3], v[6:7]
	v_rcp_f32_e32 v6, v0
	v_mul_f32_e32 v0, 0x3d372713, v5
	v_mul_f32_e32 v0, v5, v0
	v_fma_f32 v0, v5, v0, v5
	v_mul_f32_e32 v0, 0x3f4c422a, v0
	v_add_f32_e32 v0, v0, v0
	v_mul_f32_e32 v0, 0x3fb8aa3b, v0
	v_exp_f32_e32 v0, v0
	v_pk_mul_f32 v[4:5], v[4:5], 0.5 op_sel_hi:[1,0]
	v_cvt_pk_bf16_f32 v2, v2, v3
	v_add_f32_e32 v0, 1.0, v0
	v_rcp_f32_e32 v7, v0
	s_nop 0
	v_pk_fma_f32 v[6:7], v[6:7], 2.0, 1.0 op_sel_hi:[1,0,0] neg_lo:[1,0,0] neg_hi:[1,0,0]
	s_nop 0
	v_pk_add_f32 v[6:7], v[6:7], 1.0 op_sel_hi:[1,0]
	s_nop 0
	v_pk_mul_f32 v[4:5], v[4:5], v[6:7]
	s_nop 0
	v_cvt_pk_bf16_f32 v3, v4, v5
	global_store_dwordx2 v[14:15], v[2:3], off offset:96
	s_branch .LBB0_260
